# sample_ml set-up: loads of all four set-up sections issued together (one global round trip instead of five)
# speedup vs baseline: 1.0129x; 1.0029x over previous
.LBB0_559:
	v_mov_b32_e32 v11, v176
	s_lshl_b32 s4, s44, 1
	s_addk_i32 s4, 0xfe00
	v_ashrrev_i32_e32 v9, 8, v11
	v_add_u32_e32 v26, s4, v9
	v_lshlrev_b32_e32 v0, 1, v26
	v_and_b32_e32 v15, -8, v0
	v_and_b32_e32 v13, 3, v26
	v_add_u32_e32 v4, 0x2000, v15
	v_mov_b64_e32 v[28:29], s[30:31]
	v_and_b32_e32 v189, 0xff, v11
	v_mad_i64_i32 v[0:1], s[4:5], v4, s37, v[28:29]
	v_lshlrev_b32_e32 v16, 9, v13
	v_lshl_add_u64 v[2:3], v[0:1], 0, v[16:17]
	v_lshlrev_b32_e32 v6, 1, v189
	v_mov_b32_e32 v7, v17
	v_lshl_add_u64 v[2:3], v[2:3], 0, v[6:7]
	v_add_co_u32_e32 v2, vcc, s39, v2
	v_add_u32_e32 v14, 0x2001, v15
	v_addc_co_u32_e32 v3, vcc, 0, v3, vcc
	global_load_ushort v240, v[2:3], off
	v_mad_i32_i24 v188, v9, s17, 0
	v_lshl_add_u32 v19, v189, 2, v188
	v_add_u32_e32 v24, 0x2005, v15
	v_mad_i64_i32 v[40:41], s[4:5], v24, s37, v[28:29]
	v_ashrrev_i32_e32 v5, 31, v4
	v_mad_i64_i32 v[2:3], s[4:5], v14, s37, v[28:29]
	v_lshl_add_u64 v[20:21], v[2:3], 0, v[16:17]
	v_lshl_add_u64 v[20:21], v[20:21], 0, v[6:7]
	v_add_co_u32_e32 v20, vcc, s39, v20
	s_nop 1
	v_addc_co_u32_e32 v21, vcc, 0, v21, vcc
	global_load_ushort v241, v[20:21], off
	v_add_u32_e32 v10, 0x2002, v15
	v_mad_i64_i32 v[34:35], s[4:5], v10, s37, v[28:29]
	v_lshl_add_u64 v[20:21], v[34:35], 0, v[16:17]
	v_lshl_add_u64 v[20:21], v[20:21], 0, v[6:7]
	v_add_co_u32_e32 v20, vcc, s39, v20
	s_nop 1
	v_addc_co_u32_e32 v21, vcc, 0, v21, vcc
	global_load_ushort v243, v[20:21], off
	v_add_u32_e32 v8, 0x2003, v15
	v_mad_i64_i32 v[36:37], s[4:5], v8, s37, v[28:29]
	v_lshl_add_u64 v[20:21], v[36:37], 0, v[16:17]
	v_lshl_add_u64 v[20:21], v[20:21], 0, v[6:7]
	v_add_co_u32_e32 v20, vcc, s39, v20
	s_nop 1
	v_addc_co_u32_e32 v21, vcc, 0, v21, vcc
	global_load_ushort v245, v[20:21], off
	v_add_u32_e32 v12, 0x2004, v15
	v_mad_i64_i32 v[38:39], s[4:5], v12, s37, v[28:29]
	v_lshl_add_u64 v[20:21], v[38:39], 0, v[16:17]
	v_lshl_add_u64 v[20:21], v[20:21], 0, v[6:7]
	v_add_co_u32_e32 v20, vcc, s39, v20
	s_nop 1
	v_addc_co_u32_e32 v21, vcc, 0, v21, vcc
	global_load_ushort v248, v[20:21], off
	v_lshl_add_u64 v[20:21], v[40:41], 0, v[16:17]
	v_lshl_add_u64 v[20:21], v[20:21], 0, v[6:7]
	v_add_co_u32_e32 v20, vcc, s39, v20
	s_nop 1
	v_addc_co_u32_e32 v21, vcc, 0, v21, vcc
	global_load_ushort v249, v[20:21], off
	v_add_u32_e32 v22, 0x2006, v15
	v_mad_i64_i32 v[42:43], s[4:5], v22, s37, v[28:29]
	v_lshl_add_u64 v[20:21], v[42:43], 0, v[16:17]
	v_lshl_add_u64 v[20:21], v[20:21], 0, v[6:7]
	v_add_co_u32_e32 v20, vcc, s39, v20
	s_nop 1
	v_addc_co_u32_e32 v21, vcc, 0, v21, vcc
	global_load_ushort v252, v[20:21], off
	v_add_u32_e32 v20, 0x2007, v15
	v_mad_i64_i32 v[44:45], s[4:5], v20, s37, v[28:29]
	v_lshl_add_u64 v[28:29], v[44:45], 0, v[16:17]
	v_lshl_add_u64 v[28:29], v[28:29], 0, v[6:7]
	v_add_co_u32_e32 v28, vcc, 0x3000, v28
	s_nop 1
	v_addc_co_u32_e32 v29, vcc, 0, v29, vcc
	global_load_ushort v253, v[28:29], off
	v_lshlrev_b32_e32 v126, 8, v13
	v_mov_b32_e32 v127, v17
	v_lshlrev_b32_e32 v128, 9, v13
	v_mov_b32_e32 v129, v17
	v_lshl_add_u64 v[124:125], v[0:1], 0, v[128:129]
	v_lshl_add_u64 v[124:125], v[124:125], 0, v[6:7]
	v_add_co_u32_e32 v124, vcc, 0x2000, v124
	s_nop 1
	v_addc_co_u32_e32 v125, vcc, 0, v125, vcc
	global_load_ushort v116, v[124:125], off offset:2048
	v_lshl_add_u64 v[124:125], v[2:3], 0, v[128:129]
	v_lshl_add_u64 v[124:125], v[124:125], 0, v[6:7]
	v_add_co_u32_e32 v124, vcc, 0x2000, v124
	s_nop 1
	v_addc_co_u32_e32 v125, vcc, 0, v125, vcc
	global_load_ushort v117, v[124:125], off offset:2048
	v_lshl_add_u64 v[124:125], v[34:35], 0, v[128:129]
	v_lshl_add_u64 v[124:125], v[124:125], 0, v[6:7]
	v_add_co_u32_e32 v124, vcc, 0x2000, v124
	s_nop 1
	v_addc_co_u32_e32 v125, vcc, 0, v125, vcc
	global_load_ushort v118, v[124:125], off offset:2048
	v_lshl_add_u64 v[124:125], v[36:37], 0, v[128:129]
	v_lshl_add_u64 v[124:125], v[124:125], 0, v[6:7]
	v_add_co_u32_e32 v124, vcc, 0x2000, v124
	s_nop 1
	v_addc_co_u32_e32 v125, vcc, 0, v125, vcc
	global_load_ushort v119, v[124:125], off offset:2048
	v_lshl_add_u64 v[124:125], v[38:39], 0, v[128:129]
	v_lshl_add_u64 v[124:125], v[124:125], 0, v[6:7]
	v_add_co_u32_e32 v124, vcc, 0x2000, v124
	s_nop 1
	v_addc_co_u32_e32 v125, vcc, 0, v125, vcc
	global_load_ushort v120, v[124:125], off offset:2048
	v_lshl_add_u64 v[124:125], v[40:41], 0, v[128:129]
	v_lshl_add_u64 v[124:125], v[124:125], 0, v[6:7]
	v_add_co_u32_e32 v124, vcc, 0x2000, v124
	s_nop 1
	v_addc_co_u32_e32 v125, vcc, 0, v125, vcc
	global_load_ushort v121, v[124:125], off offset:2048
	v_lshl_add_u64 v[124:125], v[42:43], 0, v[128:129]
	v_lshl_add_u64 v[124:125], v[124:125], 0, v[6:7]
	v_add_co_u32_e32 v124, vcc, 0x2000, v124
	s_nop 1
	v_addc_co_u32_e32 v125, vcc, 0, v125, vcc
	global_load_ushort v122, v[124:125], off offset:2048
	v_lshl_add_u64 v[124:125], v[44:45], 0, v[128:129]
	v_lshl_add_u64 v[124:125], v[124:125], 0, v[6:7]
	v_add_co_u32_e32 v124, vcc, 0x2000, v124
	s_nop 1
	v_addc_co_u32_e32 v125, vcc, 0, v125, vcc
	global_load_ushort v123, v[124:125], off offset:2048
	s_movk_i32 s6, 0x80
	v_cmp_gt_u32_e64 s[6:7], s6, v189
	s_and_saveexec_b64 s[8:9], s[6:7]
	v_lshl_add_u64 v[124:125], v[0:1], 0, v[126:127]
	v_lshl_add_u64 v[124:125], v[124:125], 0, v[6:7]
	v_add_co_u32_e32 v124, vcc, 0x2000, v124
	s_nop 1
	v_addc_co_u32_e32 v125, vcc, 0, v125, vcc
	global_load_ushort v100, v[124:125], off
	global_load_ushort v101, v[124:125], off offset:1024
	v_lshl_add_u64 v[124:125], v[2:3], 0, v[126:127]
	v_lshl_add_u64 v[124:125], v[124:125], 0, v[6:7]
	v_add_co_u32_e32 v124, vcc, 0x2000, v124
	s_nop 1
	v_addc_co_u32_e32 v125, vcc, 0, v125, vcc
	global_load_ushort v102, v[124:125], off
	global_load_ushort v103, v[124:125], off offset:1024
	v_lshl_add_u64 v[124:125], v[34:35], 0, v[126:127]
	v_lshl_add_u64 v[124:125], v[124:125], 0, v[6:7]
	v_add_co_u32_e32 v124, vcc, 0x2000, v124
	s_nop 1
	v_addc_co_u32_e32 v125, vcc, 0, v125, vcc
	global_load_ushort v104, v[124:125], off
	global_load_ushort v105, v[124:125], off offset:1024
	v_lshl_add_u64 v[124:125], v[36:37], 0, v[126:127]
	v_lshl_add_u64 v[124:125], v[124:125], 0, v[6:7]
	v_add_co_u32_e32 v124, vcc, 0x2000, v124
	s_nop 1
	v_addc_co_u32_e32 v125, vcc, 0, v125, vcc
	global_load_ushort v106, v[124:125], off
	global_load_ushort v107, v[124:125], off offset:1024
	v_lshl_add_u64 v[124:125], v[38:39], 0, v[126:127]
	v_lshl_add_u64 v[124:125], v[124:125], 0, v[6:7]
	v_add_co_u32_e32 v124, vcc, 0x2000, v124
	s_nop 1
	v_addc_co_u32_e32 v125, vcc, 0, v125, vcc
	global_load_ushort v108, v[124:125], off
	global_load_ushort v109, v[124:125], off offset:1024
	v_lshl_add_u64 v[124:125], v[40:41], 0, v[126:127]
	v_lshl_add_u64 v[124:125], v[124:125], 0, v[6:7]
	v_add_co_u32_e32 v124, vcc, 0x2000, v124
	s_nop 1
	v_addc_co_u32_e32 v125, vcc, 0, v125, vcc
	global_load_ushort v110, v[124:125], off
	global_load_ushort v111, v[124:125], off offset:1024
	v_lshl_add_u64 v[124:125], v[42:43], 0, v[126:127]
	v_lshl_add_u64 v[124:125], v[124:125], 0, v[6:7]
	v_add_co_u32_e32 v124, vcc, 0x2000, v124
	s_nop 1
	v_addc_co_u32_e32 v125, vcc, 0, v125, vcc
	global_load_ushort v112, v[124:125], off
	global_load_ushort v113, v[124:125], off offset:1024
	v_lshl_add_u64 v[124:125], v[44:45], 0, v[126:127]
	v_lshl_add_u64 v[124:125], v[124:125], 0, v[6:7]
	v_add_co_u32_e32 v124, vcc, 0x2000, v124
	s_nop 1
	v_addc_co_u32_e32 v125, vcc, 0, v125, vcc
	global_load_ushort v114, v[124:125], off
	global_load_ushort v115, v[124:125], off offset:1024
	s_mov_b64 exec, s[8:9]
	v_cmp_gt_u32_e64 s[6:7], 8, v189
	s_and_saveexec_b64 s[8:9], s[6:7]
	v_or_b32_e32 v124, v4, v189
	v_ashrrev_i32_e32 v125, 31, v124
	v_lshlrev_b64 v[124:125], 7, v[124:125]
	v_lshl_add_u64 v[124:125], s[80:81], 0, v[124:125]
	v_lshlrev_b32_e32 v96, 2, v13
	v_mov_b32_e32 v97, v17
	v_lshl_add_u64 v[124:125], v[124:125], 0, v[96:97]
	global_load_dword v130, v[124:125], off offset:80
	global_load_dword v131, v96, s[94:95]
	global_load_dword v98, v[124:125], off offset:64
	global_load_dword v99, v96, s[92:93]
	s_mov_b64 exec, s[8:9]
	v_cmp_gt_u32_e32 vcc, 8, v189
	v_lshlrev_b32_e32 v28, 2, v13
	s_waitcnt vmcnt(0)
	v_lshlrev_b32_e32 v244, 16, v240
	v_lshlrev_b32_e32 v242, 16, v241
	ds_write2st64_b32 v19, v244, v242 offset0:96 offset1:100
	v_lshlrev_b32_e32 v246, 16, v243
	v_lshlrev_b32_e32 v247, 16, v245
	ds_write2st64_b32 v19, v246, v247 offset0:104 offset1:108
	v_lshlrev_b32_e32 v250, 16, v248
	v_lshlrev_b32_e32 v251, 16, v249
	ds_write2st64_b32 v19, v250, v251 offset0:112 offset1:116
	v_lshlrev_b32_e32 v21, 16, v252
	v_lshlrev_b32_e32 v7, 16, v253
	ds_write2st64_b32 v19, v21, v7 offset0:120 offset1:124
	s_and_saveexec_b64 s[4:5], vcc
	s_cbranch_execz .LBB0_561
	v_or_b32_e32 v30, v4, v189
	v_ashrrev_i32_e32 v31, 31, v30
	v_lshlrev_b64 v[30:31], 7, v[30:31]
	v_lshl_add_u64 v[30:31], s[80:81], 0, v[30:31]
	v_mov_b32_e32 v29, v17
	v_lshl_add_u64 v[32:33], v[30:31], 0, v[28:29]
	v_mov_b32_e32 v7, v130
	v_mov_b32_e32 v15, v131
	s_mov_b32 s6, 0xbfb8aa3b
	s_waitcnt vmcnt(0)
	v_add_f32_e32 v7, v7, v15
	v_min_f32_e32 v15, 0, v7
	v_mul_f32_e64 v7, |v7|, s6
	v_exp_f32_e32 v7, v7
	s_mov_b32 s6, 0x3f2aaaab
	v_add_f32_e32 v16, 1.0, v7
	v_add_f32_e32 v21, -1.0, v16
	v_sub_f32_e32 v23, v21, v16
	v_add_f32_e32 v23, 1.0, v23
	v_sub_f32_e32 v21, v7, v21
	v_add_f32_e32 v21, v21, v23
	v_frexp_mant_f32_e32 v23, v16
	v_cvt_f64_f32_e32 v[30:31], v16
	v_cmp_gt_f32_e32 vcc, s6, v23
	v_frexp_exp_i32_f64_e32 v23, v[30:31]
	s_mov_b32 s6, 0x3f317218
	v_subbrev_co_u32_e32 v23, vcc, 0, v23, vcc
	v_sub_u32_e32 v25, 0, v23
	v_ldexp_f32 v16, v16, v25
	v_ldexp_f32 v21, v21, v25
	v_add_f32_e32 v25, -1.0, v16
	v_add_f32_e32 v27, 1.0, v25
	v_sub_f32_e32 v27, v16, v27
	v_add_f32_e32 v27, v21, v27
	v_add_f32_e32 v29, v25, v27
	v_sub_f32_e32 v25, v29, v25
	v_sub_f32_e32 v25, v27, v25
	v_add_f32_e32 v27, 1.0, v16
	v_add_f32_e32 v30, -1.0, v27
	v_sub_f32_e32 v16, v16, v30
	v_add_f32_e32 v16, v21, v16
	v_add_f32_e32 v21, v27, v16
	v_sub_f32_e32 v27, v21, v27
	v_sub_f32_e32 v16, v16, v27
	v_rcp_f32_e32 v27, v21
	v_cvt_f32_i32_e32 v23, v23
	v_mul_f32_e32 v30, v29, v27
	v_mul_f32_e32 v31, v21, v30
	v_fma_f32 v46, v30, v21, -v31
	v_fmac_f32_e32 v46, v30, v16
	v_add_f32_e32 v47, v31, v46
	v_sub_f32_e32 v48, v29, v47
	v_sub_f32_e32 v29, v29, v48
	v_sub_f32_e32 v31, v47, v31
	v_sub_f32_e32 v29, v29, v47
	v_add_f32_e32 v25, v25, v29
	v_sub_f32_e32 v29, v31, v46
	v_add_f32_e32 v25, v29, v25
	v_add_f32_e32 v29, v48, v25
	v_mul_f32_e32 v31, v27, v29
	v_mul_f32_e32 v46, v21, v31
	v_fma_f32 v21, v31, v21, -v46
	v_fmac_f32_e32 v21, v31, v16
	v_sub_f32_e32 v16, v48, v29
	v_add_f32_e32 v16, v25, v16
	v_add_f32_e32 v25, v46, v21
	v_sub_f32_e32 v47, v29, v25
	v_sub_f32_e32 v29, v29, v47
	v_sub_f32_e32 v46, v25, v46
	v_sub_f32_e32 v25, v29, v25
	v_add_f32_e32 v16, v16, v25
	v_sub_f32_e32 v21, v46, v21
	v_add_f32_e32 v16, v21, v16
	v_add_f32_e32 v21, v30, v31
	v_add_f32_e32 v16, v47, v16
	v_sub_f32_e32 v25, v21, v30
	v_mul_f32_e32 v16, v27, v16
	v_sub_f32_e32 v25, v31, v25
	v_add_f32_e32 v16, v25, v16
	v_mul_f32_e32 v30, 0x3f317218, v23
	v_add_f32_e32 v25, v21, v16
	v_fma_f32 v31, v23, s6, -v30
	v_mul_f32_e32 v27, v25, v25
	v_fmac_f32_e32 v31, 0xb102e308, v23
	v_sub_f32_e32 v21, v25, v21
	v_fmamk_f32 v29, v27, 0x3e9b6dac, v177
	v_sub_f32_e32 v16, v16, v21
	v_add_f32_e32 v21, v30, v31
	v_fmaak_f32 v29, v27, v29, 0x3f2aaada
	v_sub_f32_e32 v23, v21, v30
	v_ldexp_f32 v30, v25, 1
	v_mul_f32_e32 v25, v25, v27
	v_mul_f32_e32 v25, v25, v29
	v_add_f32_e32 v27, v30, v25
	v_sub_f32_e32 v29, v27, v30
	v_ldexp_f32 v16, v16, 1
	v_sub_f32_e32 v25, v25, v29
	v_add_f32_e32 v16, v16, v25
	v_add_f32_e32 v25, v27, v16
	v_sub_f32_e32 v27, v25, v27
	v_sub_f32_e32 v16, v16, v27
	v_add_f32_e32 v27, v21, v25
	v_sub_f32_e32 v29, v27, v21
	v_sub_f32_e32 v30, v27, v29
	v_sub_f32_e32 v23, v31, v23
	v_sub_f32_e32 v21, v21, v30
	v_sub_f32_e32 v25, v25, v29
	v_add_f32_e32 v21, v25, v21
	v_add_f32_e32 v25, v23, v16
	v_sub_f32_e32 v29, v25, v23
	v_sub_f32_e32 v30, v25, v29
	v_sub_f32_e32 v23, v23, v30
	v_sub_f32_e32 v16, v16, v29
	v_add_f32_e32 v21, v25, v21
	v_add_f32_e32 v16, v16, v23
	v_add_f32_e32 v23, v27, v21
	v_sub_f32_e32 v25, v23, v27
	v_sub_f32_e32 v21, v21, v25
	v_add_f32_e32 v16, v16, v21
	s_mov_b32 s6, 0x7f800000
	v_add_f32_e32 v16, v23, v16
	v_cmp_neq_f32_e32 vcc, s6, v7
	s_mov_b32 s6, 0x33800000
	s_nop 0
	v_cndmask_b32_e32 v16, v184, v16, vcc
	v_cmp_ngt_f32_e32 vcc, -1.0, v7
	s_nop 1
	v_cndmask_b32_e32 v16, v185, v16, vcc
	v_cmp_neq_f32_e32 vcc, -1.0, v7
	s_nop 1
	v_cndmask_b32_e32 v16, v186, v16, vcc
	v_cmp_lt_f32_e64 vcc, |v7|, s6
	s_nop 1
	v_cndmask_b32_e32 v7, v16, v7, vcc
	v_sub_f32_e32 v30, v15, v7
	v_mov_b32_e32 v15, v98
	v_mov_b32_e32 v16, v99
	v_lshl_add_u32 v7, v189, 3, v188
	s_waitcnt vmcnt(0)
	v_add_f32_e32 v31, v15, v16
	ds_write_b64 v7, v[30:31] offset:33024
.LBB0_561:
	s_or_b64 exec, exec, s[4:5]
	s_movk_i32 s4, 0x80
	v_lshlrev_b32_e32 v30, 8, v13
	v_cmp_gt_u32_e64 s[4:5], s4, v189
	s_and_saveexec_b64 s[6:7], s[4:5]
	s_cbranch_execz .LBB0_563
	s_waitcnt vmcnt(0)
	v_lshlrev_b32_e32 v13, 16, v100
	v_mul_f32_e32 v13, 0x3db504f3, v13
	v_lshlrev_b32_e32 v15, 16, v101
	v_lshlrev_b32_e32 v16, 16, v102
	v_mul_f32_e32 v16, 0x3db504f3, v16
	ds_write2st64_b32 v19, v13, v16 offset1:2
	v_lshlrev_b32_e32 v13, 16, v103
	ds_write2st64_b32 v19, v15, v13 offset0:16 offset1:18
	v_lshlrev_b32_e32 v13, 16, v104
	v_mul_f32_e32 v13, 0x3db504f3, v13
	v_lshlrev_b32_e32 v15, 16, v105
	v_lshlrev_b32_e32 v16, 16, v106
	v_mul_f32_e32 v16, 0x3db504f3, v16
	ds_write2st64_b32 v19, v13, v16 offset0:4 offset1:6
	v_lshlrev_b32_e32 v13, 16, v107
	ds_write2st64_b32 v19, v15, v13 offset0:20 offset1:22
	v_lshlrev_b32_e32 v13, 16, v108
	v_mul_f32_e32 v13, 0x3db504f3, v13
	v_lshlrev_b32_e32 v15, 16, v109
	v_lshlrev_b32_e32 v16, 16, v110
	v_mul_f32_e32 v16, 0x3db504f3, v16
	ds_write2st64_b32 v19, v13, v16 offset0:8 offset1:10
	v_lshlrev_b32_e32 v13, 16, v111
	ds_write2st64_b32 v19, v15, v13 offset0:24 offset1:26
	v_lshlrev_b32_e32 v13, 16, v112
	v_mul_f32_e32 v13, 0x3db504f3, v13
	v_lshlrev_b32_e32 v15, 16, v113
	v_lshlrev_b32_e32 v7, 16, v114
	v_mul_f32_e32 v7, 0x3db504f3, v7
	ds_write2st64_b32 v19, v13, v7 offset0:12 offset1:14
	v_lshlrev_b32_e32 v7, 16, v115
	ds_write2st64_b32 v19, v15, v7 offset0:28 offset1:30
.LBB0_563:
	s_or_b64 exec, exec, s[6:7]
	v_lshlrev_b32_e32 v32, 1, v30
	v_mov_b32_e32 v33, v17
	v_mov_b32_e32 v7, v17
	v_ashrrev_i32_e32 v27, 31, v26
	v_lshlrev_b32_e32 v16, 2, v189
	s_mov_b32 s6, 0x10000
	v_lshlrev_b64 v[162:163], 7, v[26:27]
	v_mov_b32_e32 v164, 0
	s_nop 1
	s_nop 1
	s_nop 1
	s_nop 1
	s_nop 1
	s_nop 1
	s_nop 1
	s_waitcnt vmcnt(0)
	v_lshlrev_b32_e32 v13, 16, v116
	v_lshlrev_b32_e32 v242, 16, v117
	ds_write2st64_b32 v19, v13, v242 offset0:32 offset1:36
	v_lshlrev_b32_e32 v2, 16, v118
	v_lshlrev_b32_e32 v245, 16, v119
	ds_write2st64_b32 v19, v2, v245 offset0:40 offset1:44
	v_lshlrev_b32_e32 v2, 16, v120
	v_lshlrev_b32_e32 v248, 16, v121
	ds_write2st64_b32 v19, v2, v248 offset0:48 offset1:52
	v_lshlrev_b32_e32 v2, 16, v122
	v_lshlrev_b32_e32 v0, 16, v123
	ds_write2st64_b32 v19, v2, v0 offset0:56 offset1:60
	v_lshlrev_b64 v[0:1], 17, v[26:27]
	v_lshl_add_u64 v[0:1], s[72:73], 0, v[0:1]
	v_lshl_add_u64 v[0:1], v[0:1], 0, v[16:17]
	v_add_co_u32_e32 v2, vcc, s47, v0
	global_load_dword v40, v[0:1], off nt
	global_load_dword v41, v[0:1], off offset:1024 nt
	global_load_dword v38, v[0:1], off offset:2048 nt
	global_load_dword v39, v[0:1], off offset:3072 nt
	v_addc_co_u32_e32 v3, vcc, 0, v1, vcc
	v_add_co_u32_e32 v46, vcc, s27, v0
	s_nop 1
	v_addc_co_u32_e32 v47, vcc, 0, v1, vcc
	global_load_dword v44, v[46:47], off offset:-4096 nt
	global_load_dword v45, v[2:3], off offset:1024 nt
	global_load_dword v42, v[2:3], off offset:2048 nt
	global_load_dword v43, v[2:3], off offset:3072 nt
	global_load_dword v36, v[46:47], off nt
	global_load_dword v37, v[46:47], off offset:1024 nt
	global_load_dword v34, v[46:47], off offset:2048 nt
	global_load_dword v35, v[46:47], off offset:3072 nt
	v_add_co_u32_e32 v2, vcc, s39, v0
	s_nop 1
	v_addc_co_u32_e32 v3, vcc, 0, v1, vcc
	v_add_co_u32_e32 v54, vcc, s50, v0
	s_nop 1
	v_addc_co_u32_e32 v55, vcc, 0, v1, vcc
	global_load_dword v46, v[54:55], off offset:-4096 nt
	global_load_dword v47, v[2:3], off offset:1024 nt
	global_load_dword v52, v[2:3], off offset:2048 nt
	global_load_dword v53, v[2:3], off offset:3072 nt
	global_load_dword v50, v[54:55], off nt
	global_load_dword v51, v[54:55], off offset:1024 nt
	global_load_dword v48, v[54:55], off offset:2048 nt
	global_load_dword v49, v[54:55], off offset:3072 nt
	v_add_co_u32_e32 v2, vcc, s51, v0
	s_nop 1
	v_addc_co_u32_e32 v3, vcc, 0, v1, vcc
	v_add_co_u32_e32 v62, vcc, s82, v0
	s_nop 1
	v_addc_co_u32_e32 v63, vcc, 0, v1, vcc
	global_load_dword v60, v[62:63], off offset:-4096 nt
	global_load_dword v61, v[2:3], off offset:1024 nt
	global_load_dword v58, v[2:3], off offset:2048 nt
	global_load_dword v59, v[2:3], off offset:3072 nt
	global_load_dword v56, v[62:63], off nt
	global_load_dword v57, v[62:63], off offset:1024 nt
	global_load_dword v54, v[62:63], off offset:2048 nt
	global_load_dword v55, v[62:63], off offset:3072 nt
	v_add_co_u32_e32 v2, vcc, s83, v0
	s_nop 1
	v_addc_co_u32_e32 v3, vcc, 0, v1, vcc
	v_add_co_u32_e32 v66, vcc, s96, v0
	s_nop 1
	v_addc_co_u32_e32 v67, vcc, 0, v1, vcc
	global_load_dword v62, v[66:67], off offset:-4096 nt
	global_load_dword v63, v[2:3], off offset:1024 nt
	global_load_dword v64, v[2:3], off offset:2048 nt
	global_load_dword v65, v[2:3], off offset:3072 nt
	global_load_dword v72, v[66:67], off nt
	global_load_dword v73, v[66:67], off offset:1024 nt
	global_load_dword v70, v[66:67], off offset:2048 nt
	global_load_dword v71, v[66:67], off offset:3072 nt
	v_add_co_u32_e32 v2, vcc, s97, v0
	s_nop 1
	v_addc_co_u32_e32 v3, vcc, 0, v1, vcc
	v_add_co_u32_e32 v78, vcc, s17, v0
	s_nop 1
	v_addc_co_u32_e32 v79, vcc, 0, v1, vcc
	global_load_dword v76, v[78:79], off offset:-4096 nt
	global_load_dword v77, v[2:3], off offset:1024 nt
	global_load_dword v74, v[2:3], off offset:2048 nt
	global_load_dword v75, v[2:3], off offset:3072 nt
	global_load_dword v68, v[78:79], off nt
	global_load_dword v69, v[78:79], off offset:1024 nt
	global_load_dword v66, v[78:79], off offset:2048 nt
	global_load_dword v67, v[78:79], off offset:3072 nt
	v_add_co_u32_e32 v2, vcc, s10, v0
	s_nop 1
	v_addc_co_u32_e32 v3, vcc, 0, v1, vcc
	v_add_co_u32_e32 v86, vcc, s11, v0
	s_nop 1
	v_addc_co_u32_e32 v87, vcc, 0, v1, vcc
	global_load_dword v84, v[86:87], off offset:-4096 nt
	global_load_dword v85, v[2:3], off offset:1024 nt
	global_load_dword v82, v[2:3], off offset:2048 nt
	global_load_dword v83, v[2:3], off offset:3072 nt
	global_load_dword v80, v[86:87], off nt
	global_load_dword v81, v[86:87], off offset:1024 nt
	global_load_dword v78, v[86:87], off offset:2048 nt
	global_load_dword v79, v[86:87], off offset:3072 nt
	v_add_co_u32_e32 v2, vcc, s42, v0
	s_nop 1
	v_addc_co_u32_e32 v3, vcc, 0, v1, vcc
	v_add_co_u32_e32 v88, vcc, s18, v0
	s_nop 1
	v_addc_co_u32_e32 v89, vcc, 0, v1, vcc
	global_load_dword v86, v[88:89], off offset:-4096 nt
	global_load_dword v87, v[2:3], off offset:1024 nt
	global_load_dword v92, v[2:3], off offset:2048 nt
	global_load_dword v93, v[2:3], off offset:3072 nt
	global_load_dword v96, v[88:89], off nt
	global_load_dword v97, v[88:89], off offset:1024 nt
	global_load_dword v94, v[88:89], off offset:2048 nt
	global_load_dword v95, v[88:89], off offset:3072 nt
	v_add_co_u32_e32 v2, vcc, s19, v0
	s_nop 1
	v_addc_co_u32_e32 v3, vcc, 0, v1, vcc
	v_add_co_u32_e32 v102, vcc, s6, v0
	s_mov_b32 s6, 0x11000
	s_nop 0
	v_addc_co_u32_e32 v103, vcc, 0, v1, vcc
	global_load_dword v100, v[102:103], off offset:-4096 nt
	global_load_dword v101, v[2:3], off offset:1024 nt
	global_load_dword v98, v[2:3], off offset:2048 nt
	global_load_dword v99, v[2:3], off offset:3072 nt
	global_load_dword v90, v[102:103], off nt
	global_load_dword v91, v[102:103], off offset:1024 nt
	global_load_dword v88, v[102:103], off offset:2048 nt
	global_load_dword v89, v[102:103], off offset:3072 nt
	v_add_co_u32_e32 v2, vcc, s6, v0
	s_mov_b32 s6, 0x12000
	s_nop 0
	v_addc_co_u32_e32 v3, vcc, 0, v1, vcc
	v_add_co_u32_e32 v110, vcc, s6, v0
	s_mov_b32 s6, 0x13000
	s_nop 0
	v_addc_co_u32_e32 v111, vcc, 0, v1, vcc
	global_load_dword v108, v[110:111], off offset:-4096 nt
	global_load_dword v109, v[2:3], off offset:1024 nt
	global_load_dword v106, v[2:3], off offset:2048 nt
	global_load_dword v107, v[2:3], off offset:3072 nt
	global_load_dword v104, v[110:111], off nt
	global_load_dword v105, v[110:111], off offset:1024 nt
	global_load_dword v102, v[110:111], off offset:2048 nt
	global_load_dword v103, v[110:111], off offset:3072 nt
	v_add_co_u32_e32 v2, vcc, s6, v0
	s_mov_b32 s6, 0x14000
	s_nop 0
	v_addc_co_u32_e32 v3, vcc, 0, v1, vcc
	v_add_co_u32_e32 v118, vcc, s6, v0
	s_mov_b32 s6, 0x15000
	s_nop 0
	v_addc_co_u32_e32 v119, vcc, 0, v1, vcc
	global_load_dword v110, v[118:119], off offset:-4096 nt
	global_load_dword v111, v[2:3], off offset:1024 nt
	global_load_dword v116, v[2:3], off offset:2048 nt
	global_load_dword v117, v[2:3], off offset:3072 nt
	global_load_dword v114, v[118:119], off nt
	global_load_dword v115, v[118:119], off offset:1024 nt
	global_load_dword v112, v[118:119], off offset:2048 nt
	global_load_dword v113, v[118:119], off offset:3072 nt
	v_add_co_u32_e32 v2, vcc, s6, v0
	s_mov_b32 s6, 0x16000
	s_nop 0
	v_addc_co_u32_e32 v3, vcc, 0, v1, vcc
	v_add_co_u32_e32 v126, vcc, s6, v0
	s_mov_b32 s6, 0x17000
	s_nop 0
	v_addc_co_u32_e32 v127, vcc, 0, v1, vcc
	global_load_dword v124, v[126:127], off offset:-4096 nt
	global_load_dword v125, v[2:3], off offset:1024 nt
	global_load_dword v122, v[2:3], off offset:2048 nt
	global_load_dword v123, v[2:3], off offset:3072 nt
	global_load_dword v120, v[126:127], off nt
	global_load_dword v121, v[126:127], off offset:1024 nt
	global_load_dword v118, v[126:127], off offset:2048 nt
	global_load_dword v119, v[126:127], off offset:3072 nt
	v_add_co_u32_e32 v2, vcc, s6, v0
	s_mov_b32 s6, 0x18000
	s_nop 0
	v_addc_co_u32_e32 v3, vcc, 0, v1, vcc
	v_add_co_u32_e32 v128, vcc, s6, v0
	s_mov_b32 s6, 0x19000
	s_nop 0
	v_addc_co_u32_e32 v129, vcc, 0, v1, vcc
	global_load_dword v126, v[128:129], off offset:-4096 nt
	global_load_dword v127, v[2:3], off offset:1024 nt
	global_load_dword v132, v[2:3], off offset:2048 nt
	global_load_dword v133, v[2:3], off offset:3072 nt
	global_load_dword v136, v[128:129], off nt
	global_load_dword v137, v[128:129], off offset:1024 nt
	global_load_dword v134, v[128:129], off offset:2048 nt
	global_load_dword v135, v[128:129], off offset:3072 nt
	v_add_co_u32_e32 v2, vcc, s6, v0
	s_mov_b32 s6, 0x1a000
	s_nop 0
	v_addc_co_u32_e32 v3, vcc, 0, v1, vcc
	v_add_co_u32_e32 v142, vcc, s6, v0
	s_mov_b32 s6, 0x1b000
	s_nop 0
	v_addc_co_u32_e32 v143, vcc, 0, v1, vcc
	global_load_dword v140, v[142:143], off offset:-4096 nt
	global_load_dword v141, v[2:3], off offset:1024 nt
	global_load_dword v138, v[2:3], off offset:2048 nt
	global_load_dword v139, v[2:3], off offset:3072 nt
	global_load_dword v130, v[142:143], off nt
	global_load_dword v131, v[142:143], off offset:1024 nt
	global_load_dword v128, v[142:143], off offset:2048 nt
	global_load_dword v129, v[142:143], off offset:3072 nt
	v_add_co_u32_e32 v2, vcc, s6, v0
	s_nop 1
	v_addc_co_u32_e32 v3, vcc, 0, v1, vcc
	v_add_co_u32_e32 v150, vcc, s45, v0
	s_nop 1
	v_addc_co_u32_e32 v151, vcc, 0, v1, vcc
	global_load_dword v148, v[150:151], off offset:-4096 nt
	global_load_dword v149, v[2:3], off offset:1024 nt
	global_load_dword v146, v[2:3], off offset:2048 nt
	global_load_dword v147, v[2:3], off offset:3072 nt
	global_load_dword v144, v[150:151], off nt
	global_load_dword v145, v[150:151], off offset:1024 nt
	global_load_dword v142, v[150:151], off offset:2048 nt
	global_load_dword v143, v[150:151], off offset:3072 nt
	v_add_co_u32_e32 v2, vcc, s46, v0
	s_nop 1
	v_addc_co_u32_e32 v3, vcc, 0, v1, vcc
	v_add_co_u32_e32 v158, vcc, s14, v0
	s_nop 1
	v_addc_co_u32_e32 v159, vcc, 0, v1, vcc
	global_load_dword v150, v[158:159], off offset:-4096 nt
	global_load_dword v151, v[2:3], off offset:1024 nt
	global_load_dword v152, v[2:3], off offset:2048 nt
	global_load_dword v153, v[2:3], off offset:3072 nt
	global_load_dword v154, v[158:159], off nt
	global_load_dword v155, v[158:159], off offset:1024 nt
	global_load_dword v156, v[158:159], off offset:2048 nt
	global_load_dword v157, v[158:159], off offset:3072 nt
	v_add_co_u32_e32 v0, vcc, 0x1f000, v0
	s_nop 1
	v_addc_co_u32_e32 v1, vcc, 0, v1, vcc
	global_load_dword v158, v[0:1], off nt
	global_load_dword v159, v[0:1], off offset:1024 nt
	global_load_dword v160, v[0:1], off offset:2048 nt
	global_load_dword v161, v[0:1], off offset:3072 nt
	s_and_saveexec_b64 s[6:7], s[4:5]
	s_cbranch_execz .LBB0_565
	v_lshl_add_u64 v[0:1], v[162:163], 2, s[74:75]
	v_lshl_add_u64 v[0:1], v[0:1], 0, v[16:17]
	global_load_dword v164, v[0:1], off
